# post0/post1 gate-norm token loops: next token's three loads prefetched into a staging set (distance 1) around the unchanged arithmetic
# baseline (speedup 1.0000x reference)
.Lxg_done:
.LBB0_518:
	s_or_b64 exec, exec, s[0:1]
	v_and_b32_e32 v0, 0x78, v221
	s_movk_i32 s0, 0x4000
	v_mov_b32_e32 v9, 0
	v_cmp_gt_i32_e64 s[6:7], s0, v178
	v_ashrrev_i32_e32 v179, 31, v178
	v_lshlrev_b32_e32 v227, 2, v0
	s_barrier
	s_and_saveexec_b64 s[20:21], s[6:7]
	s_cbranch_execz .LBB0_521
	v_readlane_b32 s44, v255, 13
	v_readlane_b32 s45, v255, 14
	s_nop 4
	global_load_dwordx4 v[0:3], v227, s[44:45]
	global_load_dwordx4 v[4:7], v227, s[44:45] offset:16
	s_lshl_b32 s22, s30, 3
	v_readlane_b32 s46, v255, 15
	s_movk_i32 s0, 0x1200
	v_mov_b64_e32 v[10:11], s[28:29]
	s_ashr_i32 s23, s22, 31
	v_lshlrev_b64 v[14:15], 11, v[178:179]
	v_lshlrev_b32_e32 v8, 4, v210
	v_mad_i64_i32 v[10:11], s[0:1], v178, s0, v[10:11]
	s_mul_i32 s34, s30, 0x9000
	s_mul_hi_i32 s35, s22, 0x1200
	v_lshl_add_u64 v[12:13], s[26:27], 0, v[14:15]
	s_lshl_b64 s[40:41], s[22:23], 11
	v_lshl_add_u64 v[14:15], s[28:29], 0, v[14:15]
	s_mov_b64 s[44:45], 0
	v_mov_b32_e32 v20, 0x358637bd
	s_mov_b32 s23, 0x800000
	s_movk_i32 s46, 0x3fff
	v_mov_b32_e32 v21, v178
	v_readlane_b32 s47, v255, 16
	v_readlane_b32 s48, v255, 17
	v_readlane_b32 s49, v255, 18
	v_readlane_b32 s50, v255, 19
	v_readlane_b32 s51, v255, 20
	v_readlane_b32 s52, v255, 21
	v_readlane_b32 s53, v255, 22
	v_readlane_b32 s54, v255, 23
	v_readlane_b32 s55, v255, 24
	v_readlane_b32 s56, v255, 25
	v_readlane_b32 s57, v255, 26
	v_readlane_b32 s58, v255, 27
	v_readlane_b32 s59, v255, 28
	v_lshl_add_u64 v[112:113], v[14:15], 0, v[8:9]
	v_add_co_u32_e32 v118, vcc, 0xdc00000, v112
	v_lshl_add_u64 v[116:117], v[10:11], 0, v[8:9]
	s_nop 0
	v_addc_co_u32_e32 v119, vcc, 0, v113, vcc
	v_lshl_add_u64 v[114:115], v[12:13], 0, v[8:9]
	v_add_co_u32_e32 v116, vcc, 0x6400000, v116
	global_load_dwordx4 v[100:103], v[114:115], off offset:1024
	s_nop 0
	v_addc_co_u32_e32 v117, vcc, 0, v117, vcc
	global_load_dwordx4 v[104:107], v[118:119], off offset:1024
	global_load_dwordx4 v[108:111], v[116:117], off offset:3072
	v_lshl_add_u64 v[10:11], v[10:11], 0, s[34:35]
	v_lshl_add_u64 v[12:13], v[12:13], 0, s[40:41]
	v_lshl_add_u64 v[14:15], v[14:15], 0, s[40:41]
	s_waitcnt vmcnt(0)
.LBB0_520:
	s_waitcnt vmcnt(1)
	v_mov_b32_e32 v22, v100
	v_mov_b32_e32 v23, v101
	v_mov_b32_e32 v24, v102
	v_mov_b32_e32 v25, v103
	v_mov_b32_e32 v26, v104
	v_mov_b32_e32 v27, v105
	v_mov_b32_e32 v28, v106
	v_mov_b32_e32 v29, v107
	v_mov_b32_e32 v16, v108
	v_mov_b32_e32 v17, v109
	v_mov_b32_e32 v18, v110
	v_mov_b32_e32 v19, v111
	v_mov_b32_e32 v30, v118
	v_mov_b32_e32 v31, v119
	v_add_u32_e32 v21, s22, v21
	v_cmp_lt_i32_e64 s[0:1], s46, v21
	s_or_b64 s[44:45], s[0:1], s[44:45]
	s_mov_b64 s[4:5], exec
	s_andn2_b64 exec, exec, s[44:45]
	v_lshl_add_u64 v[112:113], v[14:15], 0, v[8:9]
	v_add_co_u32_e32 v118, vcc, 0xdc00000, v112
	v_lshl_add_u64 v[116:117], v[10:11], 0, v[8:9]
	s_nop 0
	v_addc_co_u32_e32 v119, vcc, 0, v113, vcc
	v_lshl_add_u64 v[114:115], v[12:13], 0, v[8:9]
	v_add_co_u32_e32 v116, vcc, 0x6400000, v116
	global_load_dwordx4 v[100:103], v[114:115], off offset:1024
	s_nop 0
	v_addc_co_u32_e32 v117, vcc, 0, v117, vcc
	global_load_dwordx4 v[104:107], v[118:119], off offset:1024
	global_load_dwordx4 v[108:111], v[116:117], off offset:3072
	v_lshl_add_u64 v[10:11], v[10:11], 0, s[34:35]
	v_lshl_add_u64 v[12:13], v[12:13], 0, s[40:41]
	v_lshl_add_u64 v[14:15], v[14:15], 0, s[40:41]
	s_mov_b64 exec, s[4:5]
	v_lshlrev_b32_e32 v38, 16, v22
	v_and_b32_e32 v39, 0xffff0000, v22
	v_lshlrev_b32_e32 v33, 16, v23
	v_lshlrev_b32_e32 v40, 16, v26
	v_and_b32_e32 v41, 0xffff0000, v26
	v_and_b32_e32 v32, 0xffff0000, v23
	v_lshlrev_b32_e32 v23, 16, v24
	v_and_b32_e32 v22, 0xffff0000, v24
	v_lshlrev_b32_e32 v35, 16, v25
	v_and_b32_e32 v34, 0xffff0000, v25
	v_lshlrev_b32_e32 v25, 16, v27
	v_and_b32_e32 v24, 0xffff0000, v27
	v_add_f32_e32 v38, v40, v38
	v_add_f32_e32 v39, v41, v39
	v_lshlrev_b32_e32 v40, 16, v16
	v_lshlrev_b32_e32 v27, 16, v28
	v_and_b32_e32 v26, 0xffff0000, v28
	v_lshlrev_b32_e32 v37, 16, v29
	v_and_b32_e32 v36, 0xffff0000, v29
	v_and_b32_e32 v41, 0xffff0000, v16
	v_lshlrev_b32_e32 v42, 16, v17
	v_and_b32_e32 v43, 0xffff0000, v17
	v_pk_add_f32 v[16:17], v[24:25], v[32:33]
	v_mul_f32_e32 v32, v39, v39
	v_mul_f32_e32 v33, 0xbfb8aa3b, v40
	v_lshlrev_b32_e32 v44, 16, v18
	v_and_b32_e32 v45, 0xffff0000, v18
	v_lshlrev_b32_e32 v46, 16, v19
	v_and_b32_e32 v47, 0xffff0000, v19
	v_pk_add_f32 v[18:19], v[26:27], v[22:23]
	v_pk_add_f32 v[22:23], v[36:37], v[34:35]
	v_pk_mul_f32 v[24:25], v[16:17], v[16:17]
	v_mul_f32_e32 v34, 0xbfb8aa3b, v41
	v_fmac_f32_e32 v32, v38, v38
	v_exp_f32_e32 v33, v33
	v_mul_f32_e32 v35, 0xbfb8aa3b, v42
	v_mul_f32_e32 v48, 0xbfb8aa3b, v45
	v_exp_f32_e32 v34, v34
	v_add_f32_e32 v25, v32, v25
	v_pk_mul_f32 v[26:27], v[18:19], v[18:19]
	v_mul_f32_e32 v36, 0xbfb8aa3b, v43
	v_mul_f32_e32 v50, 0xbfb8aa3b, v47
	v_exp_f32_e32 v35, v35
	v_exp_f32_e32 v48, v48
	v_add_f32_e32 v24, v24, v25
	v_mul_f32_e32 v37, 0xbfb8aa3b, v44
	v_exp_f32_e32 v36, v36
	v_exp_f32_e32 v50, v50
	v_add_f32_e32 v24, v27, v24
	v_pk_mul_f32 v[28:29], v[22:23], v[22:23]
	v_exp_f32_e32 v37, v37
	v_add_f32_e32 v24, v26, v24
	v_add_f32_e32 v25, 1.0, v33
	v_mul_f32_e32 v49, 0xbfb8aa3b, v46
	v_add_f32_e32 v26, 1.0, v34
	v_add_f32_e32 v24, v29, v24
	v_div_scale_f32 v29, s[0:1], v25, v25, v40
	v_exp_f32_e32 v49, v49
	v_add_f32_e32 v27, 1.0, v35
	v_add_f32_e32 v34, 1.0, v48
	v_div_scale_f32 v48, s[0:1], v26, v26, v41
	v_add_f32_e32 v24, v28, v24
	v_rcp_f32_e32 v28, v29
	v_add_f32_e32 v32, 1.0, v36
	v_add_f32_e32 v36, 1.0, v50
	v_div_scale_f32 v50, s[0:1], v27, v27, v42
	v_rcp_f32_e32 v62, v48
	v_add_f32_dpp v24, v24, v24 row_ror:8 row_mask:0xf bank_mask:0xf bound_ctrl:1
	v_add_f32_e32 v33, 1.0, v37
	v_div_scale_f32 v52, s[0:1], v32, v32, v43
	v_rcp_f32_e32 v63, v50
	v_add_f32_dpp v24, v24, v24 row_ror:4 row_mask:0xf bank_mask:0xf bound_ctrl:1
	v_div_scale_f32 v54, s[0:1], v33, v33, v44
	v_rcp_f32_e32 v64, v52
	v_add_f32_dpp v24, v24, v24 row_ror:2 row_mask:0xf bank_mask:0xf bound_ctrl:1
	v_add_f32_e32 v35, 1.0, v49
	v_div_scale_f32 v56, s[0:1], v34, v34, v45
	v_rcp_f32_e32 v65, v54
	v_add_f32_dpp v24, v24, v24 row_ror:1 row_mask:0xf bank_mask:0xf bound_ctrl:1
	v_fma_f32 v69, -v29, v28, 1.0
	v_div_scale_f32 v37, vcc, v40, v25, v40
	v_div_scale_f32 v58, s[0:1], v35, v35, v46
	v_rcp_f32_e32 v66, v56
	v_fma_f32 v70, -v48, v62, 1.0
	v_fmamk_f32 v24, v24, 0x3c000000, v20
	v_fmac_f32_e32 v28, v69, v28
	v_div_scale_f32 v49, s[10:11], v41, v26, v41
	v_div_scale_f32 v60, s[0:1], v36, v36, v47
	v_rcp_f32_e32 v67, v58
	v_fma_f32 v71, -v50, v63, 1.0
	v_fmac_f32_e32 v62, v70, v62
	v_mul_f32_e32 v69, 0x4b800000, v24
	v_mul_f32_e32 v70, v37, v28
	v_cmp_gt_f32_e64 s[18:19], s23, v24
	v_div_scale_f32 v51, s[12:13], v42, v27, v42
	v_rcp_f32_e32 v68, v60
	v_fma_f32 v72, -v52, v64, 1.0
	v_fmac_f32_e32 v63, v71, v63
	v_mul_f32_e32 v71, v49, v62
	v_cndmask_b32_e64 v24, v24, v69, s[18:19]
	v_fma_f32 v69, -v29, v70, v37
	v_div_scale_f32 v53, s[14:15], v43, v32, v43
	v_fma_f32 v73, -v54, v65, 1.0
	v_fmac_f32_e32 v64, v72, v64
	v_mul_f32_e32 v72, v51, v63
	v_fma_f32 v78, -v48, v71, v49
	v_rsq_f32_e32 v24, v24
	v_fmac_f32_e32 v70, v69, v28
	v_div_scale_f32 v55, s[16:17], v44, v33, v44
	v_fma_f32 v74, -v56, v66, 1.0
	v_fmac_f32_e32 v65, v73, v65
	v_mul_f32_e32 v73, v53, v64
	v_fma_f32 v79, -v50, v72, v51
	v_fmac_f32_e32 v71, v78, v62
	v_fma_f32 v29, -v29, v70, v37
	v_div_scale_f32 v57, s[8:9], v45, v34, v45
	v_fma_f32 v75, -v58, v67, 1.0
	v_fmac_f32_e32 v66, v74, v66
	v_mul_f32_e32 v74, v55, v65
	v_fma_f32 v80, -v52, v73, v53
	v_fmac_f32_e32 v72, v79, v63
	v_fma_f32 v37, -v48, v71, v49
	v_div_fmas_f32 v28, v29, v28, v70
	s_mov_b64 vcc, s[10:11]
	v_div_scale_f32 v59, s[4:5], v46, v35, v46
	v_fma_f32 v76, -v60, v68, 1.0
	v_fmac_f32_e32 v67, v75, v67
	v_mul_f32_e32 v75, v57, v66
	v_fma_f32 v81, -v54, v74, v55
	v_fmac_f32_e32 v73, v80, v64
	v_fma_f32 v48, -v50, v72, v51
	v_div_fixup_f32 v25, v28, v25, v40
	v_div_fmas_f32 v28, v37, v62, v71
	s_mov_b64 vcc, s[12:13]
	v_div_scale_f32 v61, s[0:1], v47, v36, v47
	v_fmac_f32_e32 v68, v76, v68
	v_mul_f32_e32 v76, v59, v67
	v_fma_f32 v82, -v56, v75, v57
	v_fmac_f32_e32 v74, v81, v65
	v_fma_f32 v49, -v52, v73, v53
	v_mul_f32_e32 v29, 0x45800000, v24
	v_div_fixup_f32 v26, v28, v26, v41
	v_div_fmas_f32 v28, v48, v63, v72
	s_mov_b64 vcc, s[14:15]
	v_mul_f32_e32 v77, v61, v68
	v_fma_f32 v83, -v58, v76, v59
	v_fmac_f32_e32 v75, v82, v66
	v_fma_f32 v50, -v54, v74, v55
	v_cndmask_b32_e64 v24, v24, v29, s[18:19]
	v_div_fixup_f32 v27, v28, v27, v42
	v_div_fmas_f32 v28, v49, v64, v73
	s_mov_b64 vcc, s[16:17]
	v_fma_f32 v84, -v60, v77, v61
	v_fmac_f32_e32 v76, v83, v67
	v_fma_f32 v51, -v56, v75, v57
	v_mul_f32_e32 v17, v17, v24
	v_div_fixup_f32 v28, v28, v32, v43
	v_div_fmas_f32 v32, v50, v65, v74
	s_mov_b64 vcc, s[8:9]
	v_fmac_f32_e32 v77, v84, v68
	v_fma_f32 v52, -v58, v76, v59
	v_mul_f32_e32 v29, v38, v24
	v_mul_f32_e32 v37, v39, v24
	v_mul_f32_e32 v16, v16, v24
	v_mul_f32_e32 v17, v2, v17
	v_div_fixup_f32 v32, v32, v33, v44
	v_div_fmas_f32 v33, v51, v66, v75
	s_mov_b64 vcc, s[4:5]
	v_fma_f32 v53, -v60, v77, v61
	v_mul_f32_e32 v19, v19, v24
	v_mul_f32_e32 v18, v18, v24
	v_mul_f32_e32 v23, v23, v24
	v_mul_f32_e32 v22, v22, v24
	v_mul_f32_e32 v24, v0, v29
	v_mul_f32_e32 v29, v1, v37
	v_mul_f32_e32 v16, v3, v16
	v_mul_f32_e32 v17, v27, v17
	v_div_fmas_f32 v27, v52, v67, v76
	s_mov_b64 vcc, s[0:1]
	v_mul_f32_e32 v19, v4, v19
	v_mul_f32_e32 v18, v5, v18
	v_mul_f32_e32 v24, v25, v24
	v_mul_f32_e32 v25, v26, v29
	v_mul_f32_e32 v26, v28, v16
	v_div_fixup_f32 v16, v33, v34, v45
	v_div_fmas_f32 v28, v53, v68, v77
	v_mul_f32_e32 v22, v7, v22
	v_mul_f32_e32 v19, v32, v19
	v_mul_f32_e32 v18, v16, v18
	v_cvt_pk_bf16_f32 v16, v24, v25
	v_div_fixup_f32 v24, v28, v36, v47
	v_mul_f32_e32 v23, v6, v23
	v_div_fixup_f32 v27, v27, v35, v46
	v_cvt_pk_bf16_f32 v17, v17, v26
	v_cvt_pk_bf16_f32 v18, v19, v18
	v_mul_f32_e32 v19, v24, v22
	v_mul_f32_e32 v23, v27, v23
	v_cvt_pk_bf16_f32 v19, v23, v19
	global_store_dwordx4 v[30:31], v[16:19], off offset:1024
	s_andn2_b64 exec, exec, s[44:45]
	s_cbranch_execnz .LBB0_520

.LBB0_1175:
	s_or_b64 exec, exec, s[0:1]
	s_waitcnt lgkmcnt(0)
	s_barrier
	s_and_saveexec_b64 s[20:21], s[6:7]
	s_cbranch_execz .LBB0_1178
	v_readlane_b32 s44, v255, 13
	v_readlane_b32 s52, v255, 21
	v_readlane_b32 s53, v255, 22
	v_readlane_b32 s54, v255, 23
	v_readlane_b32 s55, v255, 24
	s_mov_b64 s[12:13], s[52:53]
	global_load_dwordx4 v[0:3], v227, s[12:13]
	global_load_dwordx4 v[4:7], v227, s[12:13] offset:16
	s_lshl_b32 s24, s30, 3
	v_readlane_b32 s45, v255, 14
	v_readlane_b32 s46, v255, 15
	v_readlane_b32 s47, v255, 16
	v_readlane_b32 s48, v255, 17
	s_movk_i32 s0, 0x2200
	v_mov_b64_e32 v[10:11], s[28:29]
	s_ashr_i32 s25, s24, 31
	v_lshlrev_b64 v[14:15], 11, v[178:179]
	v_lshlrev_b32_e32 v8, 4, v210
	v_mov_b32_e32 v9, 0
	v_mad_i64_i32 v[10:11], s[0:1], v178, s0, v[10:11]
	s_mul_i32 s34, s30, 0x11000
	s_mul_hi_i32 s35, s24, 0x2200
	v_lshl_add_u64 v[12:13], s[28:29], 0, v[14:15]
	s_lshl_b64 s[44:45], s[24:25], 11
	v_lshl_add_u64 v[14:15], s[26:27], 0, v[14:15]
	s_mov_b64 s[46:47], 0
	v_mov_b32_e32 v20, 0x358637bd
	s_mov_b32 s25, 0x800000
	s_movk_i32 s48, 0x3fff
	v_readlane_b32 s49, v255, 18
	v_readlane_b32 s50, v255, 19
	v_readlane_b32 s51, v255, 20
	v_readlane_b32 s56, v255, 25
	v_readlane_b32 s57, v255, 26
	v_readlane_b32 s58, v255, 27
	v_readlane_b32 s59, v255, 28
	s_mov_b64 s[14:15], s[54:55]
	v_lshl_add_u64 v[112:113], v[12:13], 0, v[8:9]
	v_add_co_u32_e32 v118, vcc, 0xdc00000, v112
	v_lshl_add_u64 v[116:117], v[10:11], 0, v[8:9]
	s_nop 0
	v_addc_co_u32_e32 v119, vcc, 0, v113, vcc
	v_lshl_add_u64 v[114:115], v[14:15], 0, v[8:9]
	v_add_co_u32_e32 v116, vcc, 0x3401000, v116
	global_load_dwordx4 v[100:103], v[114:115], off
	s_nop 0
	v_addc_co_u32_e32 v117, vcc, 0, v117, vcc
	global_load_dwordx4 v[104:107], v[118:119], off
	global_load_dwordx4 v[108:111], v[116:117], off
	v_lshl_add_u64 v[10:11], v[10:11], 0, s[34:35]
	v_lshl_add_u64 v[12:13], v[12:13], 0, s[44:45]
	v_lshl_add_u64 v[14:15], v[14:15], 0, s[44:45]
	s_waitcnt vmcnt(0)
.LBB0_1177:
	s_waitcnt vmcnt(1)
	v_mov_b32_e32 v22, v100
	v_mov_b32_e32 v23, v101
	v_mov_b32_e32 v24, v102
	v_mov_b32_e32 v25, v103
	v_mov_b32_e32 v26, v104
	v_mov_b32_e32 v27, v105
	v_mov_b32_e32 v28, v106
	v_mov_b32_e32 v29, v107
	v_mov_b32_e32 v16, v108
	v_mov_b32_e32 v17, v109
	v_mov_b32_e32 v18, v110
	v_mov_b32_e32 v19, v111
	v_mov_b32_e32 v30, v118
	v_mov_b32_e32 v31, v119
	v_add_u32_e32 v178, s24, v178
	v_cmp_lt_i32_e64 s[0:1], s48, v178
	s_or_b64 s[46:47], s[0:1], s[46:47]
	s_mov_b64 s[6:7], exec
	s_andn2_b64 exec, exec, s[46:47]
	v_lshl_add_u64 v[112:113], v[12:13], 0, v[8:9]
	v_add_co_u32_e32 v118, vcc, 0xdc00000, v112
	v_lshl_add_u64 v[116:117], v[10:11], 0, v[8:9]
	s_nop 0
	v_addc_co_u32_e32 v119, vcc, 0, v113, vcc
	v_lshl_add_u64 v[114:115], v[14:15], 0, v[8:9]
	v_add_co_u32_e32 v116, vcc, 0x3401000, v116
	global_load_dwordx4 v[100:103], v[114:115], off
	s_nop 0
	v_addc_co_u32_e32 v117, vcc, 0, v117, vcc
	global_load_dwordx4 v[104:107], v[118:119], off
	global_load_dwordx4 v[108:111], v[116:117], off
	v_lshl_add_u64 v[10:11], v[10:11], 0, s[34:35]
	v_lshl_add_u64 v[12:13], v[12:13], 0, s[44:45]
	v_lshl_add_u64 v[14:15], v[14:15], 0, s[44:45]
	s_mov_b64 exec, s[6:7]
	v_lshlrev_b32_e32 v21, 16, v22
	v_and_b32_e32 v38, 0xffff0000, v22
	v_lshlrev_b32_e32 v33, 16, v23
	v_lshlrev_b32_e32 v39, 16, v26
	v_and_b32_e32 v40, 0xffff0000, v26
	v_and_b32_e32 v32, 0xffff0000, v23
	v_lshlrev_b32_e32 v23, 16, v24
	v_and_b32_e32 v22, 0xffff0000, v24
	v_lshlrev_b32_e32 v35, 16, v25
	v_and_b32_e32 v34, 0xffff0000, v25
	v_lshlrev_b32_e32 v25, 16, v27
	v_and_b32_e32 v24, 0xffff0000, v27
	v_add_f32_e32 v21, v39, v21
	v_add_f32_e32 v38, v40, v38
	v_lshlrev_b32_e32 v39, 16, v16
	v_lshlrev_b32_e32 v27, 16, v28
	v_and_b32_e32 v26, 0xffff0000, v28
	v_lshlrev_b32_e32 v37, 16, v29
	v_and_b32_e32 v36, 0xffff0000, v29
	v_and_b32_e32 v40, 0xffff0000, v16
	v_lshlrev_b32_e32 v41, 16, v17
	v_and_b32_e32 v42, 0xffff0000, v17
	v_pk_add_f32 v[16:17], v[24:25], v[32:33]
	v_mul_f32_e32 v32, v38, v38
	v_mul_f32_e32 v33, 0xbfb8aa3b, v39
	v_lshlrev_b32_e32 v43, 16, v18
	v_and_b32_e32 v44, 0xffff0000, v18
	v_lshlrev_b32_e32 v45, 16, v19
	v_and_b32_e32 v46, 0xffff0000, v19
	v_pk_add_f32 v[18:19], v[26:27], v[22:23]
	v_pk_add_f32 v[22:23], v[36:37], v[34:35]
	v_pk_mul_f32 v[24:25], v[16:17], v[16:17]
	v_mul_f32_e32 v34, 0xbfb8aa3b, v40
	v_fmac_f32_e32 v32, v21, v21
	v_exp_f32_e32 v33, v33
	v_mul_f32_e32 v35, 0xbfb8aa3b, v41
	v_mul_f32_e32 v47, 0xbfb8aa3b, v44
	v_exp_f32_e32 v34, v34
	v_add_f32_e32 v25, v32, v25
	v_pk_mul_f32 v[26:27], v[18:19], v[18:19]
	v_mul_f32_e32 v36, 0xbfb8aa3b, v42
	v_mul_f32_e32 v49, 0xbfb8aa3b, v46
	v_exp_f32_e32 v35, v35
	v_exp_f32_e32 v47, v47
	v_add_f32_e32 v24, v24, v25
	v_mul_f32_e32 v37, 0xbfb8aa3b, v43
	v_exp_f32_e32 v36, v36
	v_exp_f32_e32 v49, v49
	v_add_f32_e32 v24, v27, v24
	v_pk_mul_f32 v[28:29], v[22:23], v[22:23]
	v_exp_f32_e32 v37, v37
	v_add_f32_e32 v24, v26, v24
	v_add_f32_e32 v25, 1.0, v33
	v_mul_f32_e32 v48, 0xbfb8aa3b, v45
	v_add_f32_e32 v26, 1.0, v34
	v_add_f32_e32 v24, v29, v24
	v_div_scale_f32 v29, s[0:1], v25, v25, v39
	v_exp_f32_e32 v48, v48
	v_add_f32_e32 v27, 1.0, v35
	v_add_f32_e32 v34, 1.0, v47
	v_div_scale_f32 v47, s[0:1], v26, v26, v40
	v_add_f32_e32 v24, v28, v24
	v_rcp_f32_e32 v28, v29
	v_add_f32_e32 v32, 1.0, v36
	v_add_f32_e32 v36, 1.0, v49
	v_div_scale_f32 v49, s[0:1], v27, v27, v41
	v_rcp_f32_e32 v61, v47
	v_add_f32_dpp v24, v24, v24 row_ror:8 row_mask:0xf bank_mask:0xf bound_ctrl:1
	v_add_f32_e32 v33, 1.0, v37
	v_div_scale_f32 v51, s[0:1], v32, v32, v42
	v_rcp_f32_e32 v62, v49
	v_add_f32_dpp v24, v24, v24 row_ror:4 row_mask:0xf bank_mask:0xf bound_ctrl:1
	v_div_scale_f32 v53, s[0:1], v33, v33, v43
	v_rcp_f32_e32 v63, v51
	v_add_f32_dpp v24, v24, v24 row_ror:2 row_mask:0xf bank_mask:0xf bound_ctrl:1
	v_add_f32_e32 v35, 1.0, v48
	v_div_scale_f32 v55, s[0:1], v34, v34, v44
	v_rcp_f32_e32 v64, v53
	v_add_f32_dpp v24, v24, v24 row_ror:1 row_mask:0xf bank_mask:0xf bound_ctrl:1
	v_fma_f32 v68, -v29, v28, 1.0
	v_div_scale_f32 v37, vcc, v39, v25, v39
	v_div_scale_f32 v57, s[0:1], v35, v35, v45
	v_rcp_f32_e32 v65, v55
	v_fma_f32 v69, -v47, v61, 1.0
	v_fmamk_f32 v24, v24, 0x3c000000, v20
	v_fmac_f32_e32 v28, v68, v28
	v_div_scale_f32 v48, s[12:13], v40, v26, v40
	v_div_scale_f32 v59, s[0:1], v36, v36, v46
	v_rcp_f32_e32 v66, v57
	v_fma_f32 v70, -v49, v62, 1.0
	v_fmac_f32_e32 v61, v69, v61
	v_mul_f32_e32 v68, 0x4b800000, v24
	v_mul_f32_e32 v69, v37, v28
	v_cmp_gt_f32_e64 s[22:23], s25, v24
	v_div_scale_f32 v50, s[14:15], v41, v27, v41
	v_rcp_f32_e32 v67, v59
	v_fma_f32 v71, -v51, v63, 1.0
	v_fmac_f32_e32 v62, v70, v62
	v_mul_f32_e32 v70, v48, v61
	v_cndmask_b32_e64 v24, v24, v68, s[22:23]
	v_fma_f32 v68, -v29, v69, v37
	v_div_scale_f32 v52, s[16:17], v42, v32, v42
	v_fma_f32 v72, -v53, v64, 1.0
	v_fmac_f32_e32 v63, v71, v63
	v_mul_f32_e32 v71, v50, v62
	v_fma_f32 v77, -v47, v70, v48
	v_rsq_f32_e32 v24, v24
	v_fmac_f32_e32 v69, v68, v28
	v_div_scale_f32 v54, s[18:19], v43, v33, v43
	v_fma_f32 v73, -v55, v65, 1.0
	v_fmac_f32_e32 v64, v72, v64
	v_mul_f32_e32 v72, v52, v63
	v_fma_f32 v78, -v49, v71, v50
	v_fmac_f32_e32 v70, v77, v61
	v_fma_f32 v29, -v29, v69, v37
	v_div_scale_f32 v56, s[10:11], v44, v34, v44
	v_fma_f32 v74, -v57, v66, 1.0
	v_fmac_f32_e32 v65, v73, v65
	v_mul_f32_e32 v73, v54, v64
	v_fma_f32 v79, -v51, v72, v52
	v_fmac_f32_e32 v71, v78, v62
	v_fma_f32 v37, -v47, v70, v48
	v_div_fmas_f32 v28, v29, v28, v69
	s_mov_b64 vcc, s[12:13]
	v_div_scale_f32 v58, s[6:7], v45, v35, v45
	v_fma_f32 v75, -v59, v67, 1.0
	v_fmac_f32_e32 v66, v74, v66
	v_mul_f32_e32 v74, v56, v65
	v_fma_f32 v80, -v53, v73, v54
	v_fmac_f32_e32 v72, v79, v63
	v_fma_f32 v47, -v49, v71, v50
	v_div_fixup_f32 v25, v28, v25, v39
	v_div_fmas_f32 v28, v37, v61, v70
	s_mov_b64 vcc, s[14:15]
	v_div_scale_f32 v60, s[0:1], v46, v36, v46
	v_fmac_f32_e32 v67, v75, v67
	v_mul_f32_e32 v75, v58, v66
	v_fma_f32 v81, -v55, v74, v56
	v_fmac_f32_e32 v73, v80, v64
	v_fma_f32 v48, -v51, v72, v52
	v_mul_f32_e32 v29, 0x45800000, v24
	v_div_fixup_f32 v26, v28, v26, v40
	v_div_fmas_f32 v28, v47, v62, v71
	s_mov_b64 vcc, s[16:17]
	v_mul_f32_e32 v76, v60, v67
	v_fma_f32 v82, -v57, v75, v58
	v_fmac_f32_e32 v74, v81, v65
	v_fma_f32 v49, -v53, v73, v54
	v_cndmask_b32_e64 v24, v24, v29, s[22:23]
	v_div_fixup_f32 v27, v28, v27, v41
	v_div_fmas_f32 v28, v48, v63, v72
	s_mov_b64 vcc, s[18:19]
	v_fma_f32 v83, -v59, v76, v60
	v_fmac_f32_e32 v75, v82, v66
	v_fma_f32 v50, -v55, v74, v56
	v_mul_f32_e32 v29, v38, v24
	v_div_fixup_f32 v28, v28, v32, v42
	v_div_fmas_f32 v32, v49, v64, v73
	s_mov_b64 vcc, s[10:11]
	v_fmac_f32_e32 v76, v83, v67
	v_fma_f32 v51, -v57, v75, v58
	v_mul_f32_e32 v21, v21, v24
	v_mul_f32_e32 v17, v17, v24
	v_mul_f32_e32 v16, v16, v24
	v_mul_f32_e32 v19, v19, v24
	v_mul_f32_e32 v18, v18, v24
	v_mul_f32_e32 v23, v23, v24
	v_mul_f32_e32 v22, v22, v24
	v_mul_f32_e32 v24, v1, v29
	v_div_fixup_f32 v29, v32, v33, v43
	v_div_fmas_f32 v32, v50, v65, v74
	s_mov_b64 vcc, s[6:7]
	v_fma_f32 v52, -v59, v76, v60
	v_mul_f32_e32 v21, v0, v21
	v_mul_f32_e32 v17, v2, v17
	v_mul_f32_e32 v16, v3, v16
	v_mul_f32_e32 v24, v26, v24
	v_div_fmas_f32 v26, v51, v66, v75
	s_mov_b64 vcc, s[0:1]
	v_mul_f32_e32 v19, v4, v19
	v_mul_f32_e32 v18, v5, v18
	v_mul_f32_e32 v23, v6, v23
	v_mul_f32_e32 v21, v25, v21
	v_mul_f32_e32 v17, v27, v17
	v_mul_f32_e32 v25, v28, v16
	v_div_fixup_f32 v16, v32, v34, v44
	v_div_fixup_f32 v26, v26, v35, v45
	v_div_fmas_f32 v27, v52, v67, v76
	v_mul_f32_e32 v22, v7, v22
	v_mul_f32_e32 v19, v29, v19
	v_mul_f32_e32 v18, v16, v18
	v_cvt_pk_bf16_f32 v16, v21, v24
	v_mul_f32_e32 v21, v26, v23
	v_div_fixup_f32 v23, v27, v36, v46
	v_cvt_pk_bf16_f32 v17, v17, v25
	v_cvt_pk_bf16_f32 v18, v19, v18
	v_mul_f32_e32 v19, v23, v22
	v_cvt_pk_bf16_f32 v19, v21, v19
	global_store_dwordx4 v[30:31], v[16:19], off
	s_andn2_b64 exec, exec, s[46:47]
	s_cbranch_execnz .LBB0_1177
